# final combine phase: YS gather loads back to default cache policy (written one phase earlier); output stores stay streaming
# baseline (speedup 1.0000x reference)
.LBB0_1735:
	s_waitcnt vmcnt(0)
	v_readfirstlane_b32 s0, v32
	v_readfirstlane_b32 s14, v33
	s_ashr_i32 s1, s0, 31
	v_readfirstlane_b32 s18, v34
	s_lshl_b64 s[0:1], s[0:1], 12
	s_ashr_i32 s15, s14, 31
	v_readfirstlane_b32 s20, v35
	v_lshl_add_u64 v[100:101], v[134:135], 0, s[0:1]
	s_lshl_b64 s[0:1], s[14:15], 12
	s_ashr_i32 s19, s18, 31
	global_load_dwordx2 v[198:199], v[100:101], off
	global_load_dwordx2 v[196:197], v[100:101], off offset:512
	global_load_dwordx2 v[194:195], v[100:101], off offset:1024
	global_load_dwordx2 v[192:193], v[100:101], off offset:1536
	global_load_dwordx2 v[190:191], v[100:101], off offset:2048
	global_load_dwordx2 v[188:189], v[100:101], off offset:2560
	global_load_dwordx2 v[186:187], v[100:101], off offset:3072
	global_load_dwordx2 v[184:185], v[100:101], off offset:3584
	v_lshl_add_u64 v[100:101], v[134:135], 0, s[0:1]
	s_lshl_b64 s[0:1], s[18:19], 12
	s_ashr_i32 s21, s20, 31
	global_load_dwordx2 v[182:183], v[100:101], off
	global_load_dwordx2 v[180:181], v[100:101], off offset:512
	global_load_dwordx2 v[178:179], v[100:101], off offset:1024
	global_load_dwordx2 v[176:177], v[100:101], off offset:1536
	global_load_dwordx2 v[174:175], v[100:101], off offset:2048
	global_load_dwordx2 v[172:173], v[100:101], off offset:2560
	global_load_dwordx2 v[170:171], v[100:101], off offset:3072
	global_load_dwordx2 v[168:169], v[100:101], off offset:3584
	v_lshl_add_u64 v[100:101], v[134:135], 0, s[0:1]
	s_lshl_b64 s[0:1], s[20:21], 12
	global_load_dwordx2 v[166:167], v[100:101], off
	global_load_dwordx2 v[164:165], v[100:101], off offset:512
	global_load_dwordx2 v[162:163], v[100:101], off offset:1024
	global_load_dwordx2 v[160:161], v[100:101], off offset:1536
	global_load_dwordx2 v[158:159], v[100:101], off offset:2048
	global_load_dwordx2 v[156:157], v[100:101], off offset:2560
	global_load_dwordx2 v[154:155], v[100:101], off offset:3072
	global_load_dwordx2 v[152:153], v[100:101], off offset:3584
	v_lshl_add_u64 v[100:101], v[134:135], 0, s[0:1]
	s_ashr_i32 s0, s44, 31
	s_lshr_b32 s0, s0, 21
	s_add_i32 s0, s44, s0
	s_ashr_i32 s0, s0, 11
	s_mul_hi_i32 s1, s0, 0xc000
	s_mul_i32 s0, s0, 0xc000
	s_add_u32 s0, s2, s0
	s_addc_u32 s1, s3, s1
	s_add_u32 s0, s0, 0xd0a000
	s_addc_u32 s1, s1, 0
	global_load_dwordx2 v[150:151], v[100:101], off
	global_load_dwordx2 v[148:149], v[100:101], off offset:512
	global_load_dwordx2 v[146:147], v[100:101], off offset:1024
	global_load_dwordx2 v[144:145], v[100:101], off offset:1536
	global_load_dwordx2 v[142:143], v[100:101], off offset:2048
	global_load_dwordx2 v[140:141], v[100:101], off offset:2560
	global_load_dwordx2 v[138:139], v[100:101], off offset:3072
	global_load_dwordx2 v[136:137], v[100:101], off offset:3584
	global_load_dwordx4 v[128:131], v206, s[0:1]
	global_load_dwordx4 v[124:127], v207, s[0:1]
	global_load_dwordx4 v[120:123], v208, s[0:1]
	global_load_dwordx4 v[116:119], v209, s[0:1]
	global_load_dwordx4 v[112:115], v210, s[0:1]
	global_load_dwordx4 v[108:111], v211, s[0:1]
	global_load_dwordx4 v[104:107], v212, s[0:1]
	global_load_dwordx4 v[100:103], v213, s[0:1]
	s_add_i32 s44, s44, s40
	s_cmpk_gt_i32 s44, 0x3fff
	s_cselect_b64 s[14:15], -1, 0
	s_and_b64 vcc, exec, s[14:15]
	s_cbranch_vccnz .LBB0_1734
	v_lshl_add_u64 v[32:33], s[8:9], 0, v[132:133]
	v_add_co_u32_e32 v34, vcc, 0x50000000, v32
	s_nop 1
	v_addc_co_u32_e32 v35, vcc, 0, v33, vcc
	v_add_co_u32_e32 v32, vcc, 0x50001000, v32
	global_load_dwordx4 v[48:51], v[34:35], off nt
	global_load_dwordx4 v[44:47], v[34:35], off offset:1024 nt
	global_load_dwordx4 v[40:43], v[34:35], off offset:2048 nt
	global_load_dwordx4 v[36:39], v[34:35], off offset:3072 nt
	v_addc_co_u32_e32 v33, vcc, 0, v33, vcc
	global_load_dwordx4 v[64:67], v[32:33], off nt
	global_load_dwordx4 v[60:63], v[32:33], off offset:1024 nt
	global_load_dwordx4 v[56:59], v[32:33], off offset:2048 nt
	global_load_dwordx4 v[52:55], v[32:33], off offset:3072 nt
	s_nop 0
	global_load_dwordx4 v[32:35], v133, s[10:11]
	s_branch .LBB0_1734
